# P1/P8 tile boundary: the leading half-workgroup's alignment barrier moved from before its epilogue to after it, so its epilogue overlaps the trailing half's last MFMA phase
# baseline (speedup 1.0000x reference)
.LBB0_195:
	v_lshl_or_b32 v140, s28, 8, v144
	v_lshl_add_u32 v148, s29, 8, v142
	s_movk_i32 s7, 0x3800
	v_lshlrev_b32_e32 v140, 1, v140
	v_mad_u32_u24 v146, v148, s7, v140
	v_cvt_pk_bf16_f32 v124, v124, v125
	v_cvt_pk_bf16_f32 v125, v126, v127
	v_cvt_pk_bf16_f32 v126, v120, v121
	v_cvt_pk_bf16_f32 v127, v122, v123
	global_store_dwordx4 v146, v[124:127], s[68:69]
	v_cvt_pk_bf16_f32 v112, v112, v113
	v_cvt_pk_bf16_f32 v113, v114, v115
	v_cvt_pk_bf16_f32 v114, v104, v105
	v_cvt_pk_bf16_f32 v115, v106, v107
	global_store_dwordx4 v146, v[112:115], s[68:69] offset:256
	s_andn2_b64 vcc, exec, s[0:1]
	s_mov_b64 s[0:1], -1
	v_cvt_pk_bf16_f32 v104, v116, v117
	v_cvt_pk_bf16_f32 v105, v118, v119
	v_cvt_pk_bf16_f32 v106, v108, v109
	v_cvt_pk_bf16_f32 v107, v110, v111
	v_add_u32_e32 v147, 0x38000, v146
	global_store_dwordx4 v147, v[104:107], s[68:69]
	v_cvt_pk_bf16_f32 v96, v96, v97
	v_cvt_pk_bf16_f32 v97, v98, v99
	v_cvt_pk_bf16_f32 v98, v88, v89
	v_cvt_pk_bf16_f32 v99, v90, v91
	global_store_dwordx4 v147, v[96:99], s[68:69] offset:256
	v_cvt_pk_bf16_f32 v88, v100, v101
	v_cvt_pk_bf16_f32 v89, v102, v103
	v_cvt_pk_bf16_f32 v90, v92, v93
	v_cvt_pk_bf16_f32 v91, v94, v95
	v_add_u32_e32 v149, 0x70000, v146
	global_store_dwordx4 v149, v[88:91], s[68:69]
	v_cvt_pk_bf16_f32 v80, v80, v81
	v_cvt_pk_bf16_f32 v81, v82, v83
	v_cvt_pk_bf16_f32 v82, v72, v73
	v_cvt_pk_bf16_f32 v83, v74, v75
	global_store_dwordx4 v149, v[80:83], s[68:69] offset:256
	v_cvt_pk_bf16_f32 v72, v84, v85
	v_cvt_pk_bf16_f32 v73, v86, v87
	v_cvt_pk_bf16_f32 v74, v76, v77
	v_cvt_pk_bf16_f32 v75, v78, v79
	v_add_u32_e32 v147, 0xa8000, v146
	global_store_dwordx4 v147, v[72:75], s[68:69]
	v_cvt_pk_bf16_f32 v68, v68, v69
	v_cvt_pk_bf16_f32 v69, v70, v71
	v_cvt_pk_bf16_f32 v70, v64, v65
	v_cvt_pk_bf16_f32 v71, v66, v67
	global_store_dwordx4 v147, v[68:71], s[68:69] offset:256
	v_cvt_pk_bf16_f32 v60, v60, v61
	v_cvt_pk_bf16_f32 v61, v62, v63
	v_cvt_pk_bf16_f32 v62, v56, v57
	v_cvt_pk_bf16_f32 v63, v58, v59
	v_add_u32_e32 v149, 0x1c0000, v146
	global_store_dwordx4 v149, v[60:63], s[68:69]
	v_cvt_pk_bf16_f32 v48, v48, v49
	v_cvt_pk_bf16_f32 v49, v50, v51
	v_cvt_pk_bf16_f32 v50, v40, v41
	v_cvt_pk_bf16_f32 v51, v42, v43
	global_store_dwordx4 v149, v[48:51], s[68:69] offset:256
	v_cvt_pk_bf16_f32 v40, v52, v53
	v_cvt_pk_bf16_f32 v41, v54, v55
	v_cvt_pk_bf16_f32 v42, v44, v45
	v_cvt_pk_bf16_f32 v43, v46, v47
	v_add_u32_e32 v147, 0x1f8000, v146
	global_store_dwordx4 v147, v[40:43], s[68:69]
	v_cvt_pk_bf16_f32 v32, v32, v33
	v_cvt_pk_bf16_f32 v33, v34, v35
	v_cvt_pk_bf16_f32 v34, v24, v25
	v_cvt_pk_bf16_f32 v35, v26, v27
	global_store_dwordx4 v147, v[32:35], s[68:69] offset:256
	v_cvt_pk_bf16_f32 v24, v36, v37
	v_cvt_pk_bf16_f32 v25, v38, v39
	v_cvt_pk_bf16_f32 v26, v28, v29
	v_cvt_pk_bf16_f32 v27, v30, v31
	v_add_u32_e32 v149, 0x230000, v146
	global_store_dwordx4 v149, v[24:27], s[68:69]
	v_cvt_pk_bf16_f32 v16, v16, v17
	v_cvt_pk_bf16_f32 v17, v18, v19
	v_cvt_pk_bf16_f32 v18, v8, v9
	v_cvt_pk_bf16_f32 v19, v10, v11
	global_store_dwordx4 v149, v[16:19], s[68:69] offset:256
	v_cvt_pk_bf16_f32 v8, v20, v21
	v_cvt_pk_bf16_f32 v9, v22, v23
	v_cvt_pk_bf16_f32 v10, v12, v13
	v_cvt_pk_bf16_f32 v11, v14, v15
	v_add_u32_e32 v147, 0x268000, v146
	global_store_dwordx4 v147, v[8:11], s[68:69]
	v_cvt_pk_bf16_f32 v4, v4, v5
	v_cvt_pk_bf16_f32 v5, v6, v7
	v_cvt_pk_bf16_f32 v6, v0, v1
	v_cvt_pk_bf16_f32 v7, v2, v3
	global_store_dwordx4 v147, v[4:7], s[68:69] offset:256
	s_and_b64 s[98:99], exec, s[4:5]
	s_cbranch_scc0 .Lmy_nob_p1
	s_barrier
.Lmy_nob_p1:
	s_cbranch_vccnz .LBB0_188
	s_andn2_b64 vcc, exec, s[2:3]
	s_cbranch_vccnz .LBB0_187
	s_barrier
	s_branch .LBB0_187

.LBB0_1513:
	s_andn2_b64 vcc, exec, s[0:1]
	s_mov_b32 s98, 0xbfb8aa3b
	s_mov_b32 s99, 0xbfb8aa3b
	s_mov_b32 s100, 1.0
	s_mov_b32 s101, 1.0
	s_movk_i32 s7, 0x2c00
	v_lshl_or_b32 v146, s28, 7, v142
	v_lshl_add_u32 v144, s29, 8, v140
	v_lshlrev_b32_e32 v146, 1, v146
	v_mad_u32_u24 v148, v144, s7, v146
	v_pk_mul_f32 v[162:163], v[124:125], s[98:99]
	v_pk_mul_f32 v[164:165], v[126:127], s[98:99]
	v_pk_mul_f32 v[166:167], v[116:117], s[98:99]
	v_pk_mul_f32 v[168:169], v[118:119], s[98:99]
	v_exp_f32_e32 v162, v162
	v_exp_f32_e32 v163, v163
	v_exp_f32_e32 v164, v164
	v_exp_f32_e32 v165, v165
	v_exp_f32_e32 v166, v166
	v_exp_f32_e32 v167, v167
	v_exp_f32_e32 v168, v168
	v_exp_f32_e32 v169, v169
	v_pk_add_f32 v[162:163], v[162:163], s[100:101]
	v_pk_add_f32 v[164:165], v[164:165], s[100:101]
	v_pk_add_f32 v[166:167], v[166:167], s[100:101]
	v_pk_add_f32 v[168:169], v[168:169], s[100:101]
	v_rcp_f32_e32 v162, v162
	v_rcp_f32_e32 v163, v163
	v_rcp_f32_e32 v164, v164
	v_rcp_f32_e32 v165, v165
	v_rcp_f32_e32 v166, v166
	v_rcp_f32_e32 v167, v167
	v_rcp_f32_e32 v168, v168
	v_rcp_f32_e32 v169, v169
	v_pk_mul_f32 v[162:163], v[124:125], v[162:163]
	v_pk_mul_f32 v[164:165], v[126:127], v[164:165]
	v_pk_mul_f32 v[166:167], v[116:117], v[166:167]
	v_pk_mul_f32 v[168:169], v[118:119], v[168:169]
	v_pk_mul_f32 v[162:163], v[162:163], v[120:121]
	v_pk_mul_f32 v[164:165], v[164:165], v[122:123]
	v_pk_mul_f32 v[166:167], v[166:167], v[112:113]
	v_pk_mul_f32 v[168:169], v[168:169], v[114:115]
	v_cvt_pk_bf16_f32 v124, v162, v163
	v_cvt_pk_bf16_f32 v125, v164, v165
	v_cvt_pk_bf16_f32 v126, v166, v167
	v_cvt_pk_bf16_f32 v127, v168, v169
	global_store_dwordx4 v148, v[124:127], s[68:69]
	v_pk_mul_f32 v[170:171], v[108:109], s[98:99]
	v_pk_mul_f32 v[172:173], v[110:111], s[98:99]
	v_pk_mul_f32 v[174:175], v[100:101], s[98:99]
	v_pk_mul_f32 v[176:177], v[102:103], s[98:99]
	v_exp_f32_e32 v170, v170
	v_exp_f32_e32 v171, v171
	v_exp_f32_e32 v172, v172
	v_exp_f32_e32 v173, v173
	v_exp_f32_e32 v174, v174
	v_exp_f32_e32 v175, v175
	v_exp_f32_e32 v176, v176
	v_exp_f32_e32 v177, v177
	v_pk_add_f32 v[170:171], v[170:171], s[100:101]
	v_pk_add_f32 v[172:173], v[172:173], s[100:101]
	v_pk_add_f32 v[174:175], v[174:175], s[100:101]
	v_pk_add_f32 v[176:177], v[176:177], s[100:101]
	v_rcp_f32_e32 v170, v170
	v_rcp_f32_e32 v171, v171
	v_rcp_f32_e32 v172, v172
	v_rcp_f32_e32 v173, v173
	v_rcp_f32_e32 v174, v174
	v_rcp_f32_e32 v175, v175
	v_rcp_f32_e32 v176, v176
	v_rcp_f32_e32 v177, v177
	v_pk_mul_f32 v[170:171], v[108:109], v[170:171]
	v_pk_mul_f32 v[172:173], v[110:111], v[172:173]
	v_pk_mul_f32 v[174:175], v[100:101], v[174:175]
	v_pk_mul_f32 v[176:177], v[102:103], v[176:177]
	v_pk_mul_f32 v[170:171], v[170:171], v[104:105]
	v_pk_mul_f32 v[172:173], v[172:173], v[106:107]
	v_pk_mul_f32 v[174:175], v[174:175], v[96:97]
	v_pk_mul_f32 v[176:177], v[176:177], v[98:99]
	v_cvt_pk_bf16_f32 v108, v170, v171
	v_cvt_pk_bf16_f32 v109, v172, v173
	v_cvt_pk_bf16_f32 v110, v174, v175
	v_cvt_pk_bf16_f32 v111, v176, v177
	v_add_u32_e32 v149, 0x2c000, v148
	global_store_dwordx4 v149, v[108:111], s[68:69]
	v_pk_mul_f32 v[162:163], v[92:93], s[98:99]
	v_pk_mul_f32 v[164:165], v[94:95], s[98:99]
	v_pk_mul_f32 v[166:167], v[84:85], s[98:99]
	v_pk_mul_f32 v[168:169], v[86:87], s[98:99]
	v_exp_f32_e32 v162, v162
	v_exp_f32_e32 v163, v163
	v_exp_f32_e32 v164, v164
	v_exp_f32_e32 v165, v165
	v_exp_f32_e32 v166, v166
	v_exp_f32_e32 v167, v167
	v_exp_f32_e32 v168, v168
	v_exp_f32_e32 v169, v169
	v_pk_add_f32 v[162:163], v[162:163], s[100:101]
	v_pk_add_f32 v[164:165], v[164:165], s[100:101]
	v_pk_add_f32 v[166:167], v[166:167], s[100:101]
	v_pk_add_f32 v[168:169], v[168:169], s[100:101]
	v_rcp_f32_e32 v162, v162
	v_rcp_f32_e32 v163, v163
	v_rcp_f32_e32 v164, v164
	v_rcp_f32_e32 v165, v165
	v_rcp_f32_e32 v166, v166
	v_rcp_f32_e32 v167, v167
	v_rcp_f32_e32 v168, v168
	v_rcp_f32_e32 v169, v169
	v_pk_mul_f32 v[162:163], v[92:93], v[162:163]
	v_pk_mul_f32 v[164:165], v[94:95], v[164:165]
	v_pk_mul_f32 v[166:167], v[84:85], v[166:167]
	v_pk_mul_f32 v[168:169], v[86:87], v[168:169]
	v_pk_mul_f32 v[162:163], v[162:163], v[88:89]
	v_pk_mul_f32 v[164:165], v[164:165], v[90:91]
	v_pk_mul_f32 v[166:167], v[166:167], v[80:81]
	v_pk_mul_f32 v[168:169], v[168:169], v[82:83]
	v_cvt_pk_bf16_f32 v92, v162, v163
	v_cvt_pk_bf16_f32 v93, v164, v165
	v_cvt_pk_bf16_f32 v94, v166, v167
	v_cvt_pk_bf16_f32 v95, v168, v169
	v_add_u32_e32 v147, 0x58000, v148
	global_store_dwordx4 v147, v[92:95], s[68:69]
	v_pk_mul_f32 v[170:171], v[76:77], s[98:99]
	v_pk_mul_f32 v[172:173], v[78:79], s[98:99]
	v_pk_mul_f32 v[174:175], v[68:69], s[98:99]
	v_pk_mul_f32 v[176:177], v[70:71], s[98:99]
	v_exp_f32_e32 v170, v170
	v_exp_f32_e32 v171, v171
	v_exp_f32_e32 v172, v172
	v_exp_f32_e32 v173, v173
	v_exp_f32_e32 v174, v174
	v_exp_f32_e32 v175, v175
	v_exp_f32_e32 v176, v176
	v_exp_f32_e32 v177, v177
	v_pk_add_f32 v[170:171], v[170:171], s[100:101]
	v_pk_add_f32 v[172:173], v[172:173], s[100:101]
	v_pk_add_f32 v[174:175], v[174:175], s[100:101]
	v_pk_add_f32 v[176:177], v[176:177], s[100:101]
	v_rcp_f32_e32 v170, v170
	v_rcp_f32_e32 v171, v171
	v_rcp_f32_e32 v172, v172
	v_rcp_f32_e32 v173, v173
	v_rcp_f32_e32 v174, v174
	v_rcp_f32_e32 v175, v175
	v_rcp_f32_e32 v176, v176
	v_rcp_f32_e32 v177, v177
	v_pk_mul_f32 v[170:171], v[76:77], v[170:171]
	v_pk_mul_f32 v[172:173], v[78:79], v[172:173]
	v_pk_mul_f32 v[174:175], v[68:69], v[174:175]
	v_pk_mul_f32 v[176:177], v[70:71], v[176:177]
	v_pk_mul_f32 v[170:171], v[170:171], v[72:73]
	v_pk_mul_f32 v[172:173], v[172:173], v[74:75]
	v_pk_mul_f32 v[174:175], v[174:175], v[64:65]
	v_pk_mul_f32 v[176:177], v[176:177], v[66:67]
	v_cvt_pk_bf16_f32 v76, v170, v171
	v_cvt_pk_bf16_f32 v77, v172, v173
	v_cvt_pk_bf16_f32 v78, v174, v175
	v_cvt_pk_bf16_f32 v79, v176, v177
	v_add_u32_e32 v149, 0x84000, v148
	global_store_dwordx4 v149, v[76:79], s[68:69]
	v_pk_mul_f32 v[162:163], v[60:61], s[98:99]
	v_pk_mul_f32 v[164:165], v[62:63], s[98:99]
	v_pk_mul_f32 v[166:167], v[52:53], s[98:99]
	v_pk_mul_f32 v[168:169], v[54:55], s[98:99]
	v_exp_f32_e32 v162, v162
	v_exp_f32_e32 v163, v163
	v_exp_f32_e32 v164, v164
	v_exp_f32_e32 v165, v165
	v_exp_f32_e32 v166, v166
	v_exp_f32_e32 v167, v167
	v_exp_f32_e32 v168, v168
	v_exp_f32_e32 v169, v169
	v_pk_add_f32 v[162:163], v[162:163], s[100:101]
	v_pk_add_f32 v[164:165], v[164:165], s[100:101]
	v_pk_add_f32 v[166:167], v[166:167], s[100:101]
	v_pk_add_f32 v[168:169], v[168:169], s[100:101]
	v_rcp_f32_e32 v162, v162
	v_rcp_f32_e32 v163, v163
	v_rcp_f32_e32 v164, v164
	v_rcp_f32_e32 v165, v165
	v_rcp_f32_e32 v166, v166
	v_rcp_f32_e32 v167, v167
	v_rcp_f32_e32 v168, v168
	v_rcp_f32_e32 v169, v169
	v_pk_mul_f32 v[162:163], v[60:61], v[162:163]
	v_pk_mul_f32 v[164:165], v[62:63], v[164:165]
	v_pk_mul_f32 v[166:167], v[52:53], v[166:167]
	v_pk_mul_f32 v[168:169], v[54:55], v[168:169]
	v_pk_mul_f32 v[162:163], v[162:163], v[56:57]
	v_pk_mul_f32 v[164:165], v[164:165], v[58:59]
	v_pk_mul_f32 v[166:167], v[166:167], v[48:49]
	v_pk_mul_f32 v[168:169], v[168:169], v[50:51]
	v_cvt_pk_bf16_f32 v60, v162, v163
	v_cvt_pk_bf16_f32 v61, v164, v165
	v_cvt_pk_bf16_f32 v62, v166, v167
	v_cvt_pk_bf16_f32 v63, v168, v169
	v_add_u32_e32 v147, 0x160000, v148
	global_store_dwordx4 v147, v[60:63], s[68:69]
	v_pk_mul_f32 v[170:171], v[44:45], s[98:99]
	v_pk_mul_f32 v[172:173], v[46:47], s[98:99]
	v_pk_mul_f32 v[174:175], v[36:37], s[98:99]
	v_pk_mul_f32 v[176:177], v[38:39], s[98:99]
	v_exp_f32_e32 v170, v170
	v_exp_f32_e32 v171, v171
	v_exp_f32_e32 v172, v172
	v_exp_f32_e32 v173, v173
	v_exp_f32_e32 v174, v174
	v_exp_f32_e32 v175, v175
	v_exp_f32_e32 v176, v176
	v_exp_f32_e32 v177, v177
	v_pk_add_f32 v[170:171], v[170:171], s[100:101]
	v_pk_add_f32 v[172:173], v[172:173], s[100:101]
	v_pk_add_f32 v[174:175], v[174:175], s[100:101]
	v_pk_add_f32 v[176:177], v[176:177], s[100:101]
	v_rcp_f32_e32 v170, v170
	v_rcp_f32_e32 v171, v171
	v_rcp_f32_e32 v172, v172
	v_rcp_f32_e32 v173, v173
	v_rcp_f32_e32 v174, v174
	v_rcp_f32_e32 v175, v175
	v_rcp_f32_e32 v176, v176
	v_rcp_f32_e32 v177, v177
	v_pk_mul_f32 v[170:171], v[44:45], v[170:171]
	v_pk_mul_f32 v[172:173], v[46:47], v[172:173]
	v_pk_mul_f32 v[174:175], v[36:37], v[174:175]
	v_pk_mul_f32 v[176:177], v[38:39], v[176:177]
	v_pk_mul_f32 v[170:171], v[170:171], v[40:41]
	v_pk_mul_f32 v[172:173], v[172:173], v[42:43]
	v_pk_mul_f32 v[174:175], v[174:175], v[32:33]
	v_pk_mul_f32 v[176:177], v[176:177], v[34:35]
	v_cvt_pk_bf16_f32 v44, v170, v171
	v_cvt_pk_bf16_f32 v45, v172, v173
	v_cvt_pk_bf16_f32 v46, v174, v175
	v_cvt_pk_bf16_f32 v47, v176, v177
	v_add_u32_e32 v149, 0x18c000, v148
	global_store_dwordx4 v149, v[44:47], s[68:69]
	v_pk_mul_f32 v[162:163], v[28:29], s[98:99]
	v_pk_mul_f32 v[164:165], v[30:31], s[98:99]
	v_pk_mul_f32 v[166:167], v[20:21], s[98:99]
	v_pk_mul_f32 v[168:169], v[22:23], s[98:99]
	v_exp_f32_e32 v162, v162
	v_exp_f32_e32 v163, v163
	v_exp_f32_e32 v164, v164
	v_exp_f32_e32 v165, v165
	v_exp_f32_e32 v166, v166
	v_exp_f32_e32 v167, v167
	v_exp_f32_e32 v168, v168
	v_exp_f32_e32 v169, v169
	v_pk_add_f32 v[162:163], v[162:163], s[100:101]
	v_pk_add_f32 v[164:165], v[164:165], s[100:101]
	v_pk_add_f32 v[166:167], v[166:167], s[100:101]
	v_pk_add_f32 v[168:169], v[168:169], s[100:101]
	v_rcp_f32_e32 v162, v162
	v_rcp_f32_e32 v163, v163
	v_rcp_f32_e32 v164, v164
	v_rcp_f32_e32 v165, v165
	v_rcp_f32_e32 v166, v166
	v_rcp_f32_e32 v167, v167
	v_rcp_f32_e32 v168, v168
	v_rcp_f32_e32 v169, v169
	v_pk_mul_f32 v[162:163], v[28:29], v[162:163]
	v_pk_mul_f32 v[164:165], v[30:31], v[164:165]
	v_pk_mul_f32 v[166:167], v[20:21], v[166:167]
	v_pk_mul_f32 v[168:169], v[22:23], v[168:169]
	v_pk_mul_f32 v[162:163], v[162:163], v[24:25]
	v_pk_mul_f32 v[164:165], v[164:165], v[26:27]
	v_pk_mul_f32 v[166:167], v[166:167], v[16:17]
	v_pk_mul_f32 v[168:169], v[168:169], v[18:19]
	v_cvt_pk_bf16_f32 v28, v162, v163
	v_cvt_pk_bf16_f32 v29, v164, v165
	v_cvt_pk_bf16_f32 v30, v166, v167
	v_cvt_pk_bf16_f32 v31, v168, v169
	v_add_u32_e32 v147, 0x1b8000, v148
	global_store_dwordx4 v147, v[28:31], s[68:69]
	v_pk_mul_f32 v[170:171], v[12:13], s[98:99]
	v_pk_mul_f32 v[172:173], v[14:15], s[98:99]
	v_pk_mul_f32 v[174:175], v[4:5], s[98:99]
	v_pk_mul_f32 v[176:177], v[6:7], s[98:99]
	v_exp_f32_e32 v170, v170
	v_exp_f32_e32 v171, v171
	v_exp_f32_e32 v172, v172
	v_exp_f32_e32 v173, v173
	v_exp_f32_e32 v174, v174
	v_exp_f32_e32 v175, v175
	v_exp_f32_e32 v176, v176
	v_exp_f32_e32 v177, v177
	v_pk_add_f32 v[170:171], v[170:171], s[100:101]
	v_pk_add_f32 v[172:173], v[172:173], s[100:101]
	v_pk_add_f32 v[174:175], v[174:175], s[100:101]
	v_pk_add_f32 v[176:177], v[176:177], s[100:101]
	v_rcp_f32_e32 v170, v170
	v_rcp_f32_e32 v171, v171
	v_rcp_f32_e32 v172, v172
	v_rcp_f32_e32 v173, v173
	v_rcp_f32_e32 v174, v174
	v_rcp_f32_e32 v175, v175
	v_rcp_f32_e32 v176, v176
	v_rcp_f32_e32 v177, v177
	v_pk_mul_f32 v[170:171], v[12:13], v[170:171]
	v_pk_mul_f32 v[172:173], v[14:15], v[172:173]
	v_pk_mul_f32 v[174:175], v[4:5], v[174:175]
	v_pk_mul_f32 v[176:177], v[6:7], v[176:177]
	v_pk_mul_f32 v[170:171], v[170:171], v[8:9]
	v_pk_mul_f32 v[172:173], v[172:173], v[10:11]
	v_pk_mul_f32 v[174:175], v[174:175], v[0:1]
	v_pk_mul_f32 v[176:177], v[176:177], v[2:3]
	v_cvt_pk_bf16_f32 v12, v170, v171
	v_cvt_pk_bf16_f32 v13, v172, v173
	v_cvt_pk_bf16_f32 v14, v174, v175
	v_cvt_pk_bf16_f32 v15, v176, v177
	v_add_u32_e32 v149, 0x1e4000, v148
	global_store_dwordx4 v149, v[12:15], s[68:69]
	s_mov_b64 s[14:15], -1
	s_and_b64 s[98:99], exec, s[4:5]
	s_cbranch_scc0 .Lmy_nob_p8
	s_barrier
